# keep_v9 + FFN-norm sum-of-squares reduction by DPP row ops + readlane instead of six ds_bpermute round trips (f32, only the in-wave addition order changes)
# speedup vs baseline: 1.0057x; 1.0057x over previous
.Lnf_join:
	v_mul_f32_e32 v40, v18, v18
	v_mul_f32_e32 v44, v19, v19
	v_mul_f32_e32 v42, v20, v20
	v_mul_f32_e32 v38, v21, v21
	v_pk_add_f32 v[40:41], v[40:41], v[44:45]
	v_pk_add_f32 v[38:39], v[42:43], v[38:39]
	s_min_i32 s2, s24, 0x8000
	v_pk_add_f32 v[38:39], v[40:41], v[38:39]
	s_ashr_i32 s2, s2, 11
	v_add_f32_e32 v0, v38, v39
	s_add_i32 s24, s24, s10
	s_nop 0
	v_add_f32_dpp v0, v0, v0 quad_perm:[1,0,3,2] row_mask:0xf bank_mask:0xf
	s_nop 1
	v_add_f32_dpp v0, v0, v0 quad_perm:[2,3,0,1] row_mask:0xf bank_mask:0xf
	s_nop 1
	v_add_f32_dpp v0, v0, v0 row_half_mirror row_mask:0xf bank_mask:0xf
	s_nop 1
	v_add_f32_dpp v0, v0, v0 row_mirror row_mask:0xf bank_mask:0xf
	s_nop 1
	v_add_f32_dpp v0, v0, v0 row_bcast:15 row_mask:0xa bank_mask:0xf
	s_nop 1
	v_add_f32_dpp v0, v0, v0 row_bcast:31 row_mask:0xc bank_mask:0xf
	s_nop 1
	v_readlane_b32 s2, v0, 63
	s_cmp_lt_i32 s24, s20
	s_nop 1
	v_mov_b32_e32 v0, s2
	v_fmamk_f32 v0, v0, 0x3a800000, v240
	v_cmp_gt_f32_e32 vcc, s77, v0
	v_mul_f32_e32 v38, 0x4f800000, v0
	s_nop 0
	v_cndmask_b32_e32 v0, v0, v38, vcc
	v_sqrt_f32_e32 v38, v0
	s_nop 0
	v_add_u32_e32 v39, -1, v38
	v_fma_f32 v40, -v39, v38, v0
	v_cmp_ge_f32_e64 s[2:3], 0, v40
	v_add_u32_e32 v40, 1, v38
	s_nop 0
	v_cndmask_b32_e64 v39, v38, v39, s[2:3]
	v_fma_f32 v38, -v40, v38, v0
	v_cmp_lt_f32_e64 s[2:3], 0, v38
	s_nop 1
	v_cndmask_b32_e64 v38, v39, v40, s[2:3]
	v_mul_f32_e32 v39, 0x37800000, v38
	v_cndmask_b32_e32 v38, v38, v39, vcc
	v_cmp_class_f32_e32 vcc, v0, v241
	s_nop 1
	v_cndmask_b32_e32 v0, v38, v0, vcc
	v_div_scale_f32 v38, s[2:3], v0, v0, 1.0
	v_rcp_f32_e32 v39, v38
	s_nop 0
	v_fma_f32 v40, -v38, v39, 1.0
	v_fmac_f32_e32 v39, v40, v39
	v_div_scale_f32 v40, vcc, 1.0, v0, 1.0
	v_mul_f32_e32 v41, v40, v39
	v_fma_f32 v42, -v38, v41, v40
	v_fmac_f32_e32 v41, v42, v39
	v_fma_f32 v38, -v38, v41, v40
	v_div_fmas_f32 v38, v38, v39, v41
	v_div_fixup_f32 v0, v38, v0, 1.0
	v_pk_mul_f32 v[32:33], v[32:33], v[0:1] op_sel_hi:[1,0]
	v_pk_mul_f32 v[30:31], v[30:31], v[0:1] op_sel_hi:[1,0]
	v_pk_mul_f32 v[32:33], v[4:5], v[32:33]
	v_pk_mul_f32 v[30:31], v[2:3], v[30:31]
	v_pk_mul_f32 v[28:29], v[28:29], v[0:1] op_sel_hi:[1,0]
	v_pk_mul_f32 v[26:27], v[26:27], v[0:1] op_sel_hi:[1,0]
	v_pk_mul_f32 v[28:29], v[8:9], v[28:29]
	v_pk_mul_f32 v[26:27], v[6:7], v[26:27]
	v_pk_mul_f32 v[24:25], v[24:25], v[0:1] op_sel_hi:[1,0]
	v_pk_mul_f32 v[22:23], v[22:23], v[0:1] op_sel_hi:[1,0]
	v_pk_mul_f32 v[24:25], v[12:13], v[24:25]
	v_pk_mul_f32 v[22:23], v[10:11], v[22:23]
	v_pk_mul_f32 v[20:21], v[20:21], v[0:1] op_sel_hi:[1,0]
	v_pk_mul_f32 v[18:19], v[18:19], v[0:1] op_sel_hi:[1,0]
	v_pk_mul_f32 v[20:21], v[16:17], v[20:21]
	v_pk_mul_f32 v[18:19], v[14:15], v[18:19]
	s_waitcnt vmcnt(4)
	v_pk_add_f32 v[118:119], v[118:119], 1.0 op_sel_hi:[1,0]
	v_pk_add_f32 v[116:117], v[116:117], 1.0 op_sel_hi:[1,0]
	v_pk_add_f32 v[122:123], v[122:123], 1.0 op_sel_hi:[1,0]
	v_pk_add_f32 v[120:121], v[120:121], 1.0 op_sel_hi:[1,0]
	v_pk_fma_f32 v[32:33], v[118:119], v[32:33], v[102:103]
	v_pk_fma_f32 v[30:31], v[116:117], v[30:31], v[100:101]
	v_pk_add_f32 v[126:127], v[126:127], 1.0 op_sel_hi:[1,0]
	v_pk_add_f32 v[124:125], v[124:125], 1.0 op_sel_hi:[1,0]
	v_cvt_pk_bf16_f32 v30, v30, v31
	v_cvt_pk_bf16_f32 v31, v32, v33
	global_store_dwordx2 v[36:37], v[30:31], off
	v_pk_fma_f32 v[28:29], v[122:123], v[28:29], v[106:107]
	v_pk_fma_f32 v[26:27], v[120:121], v[26:27], v[104:105]
	v_pk_add_f32 v[130:131], v[130:131], 1.0 op_sel_hi:[1,0]
	v_pk_add_f32 v[128:129], v[128:129], 1.0 op_sel_hi:[1,0]
	v_cvt_pk_bf16_f32 v26, v26, v27
	v_cvt_pk_bf16_f32 v27, v28, v29
	global_store_dwordx2 v[36:37], v[26:27], off offset:512
	v_pk_fma_f32 v[24:25], v[126:127], v[24:25], v[110:111]
	v_pk_fma_f32 v[22:23], v[124:125], v[22:23], v[108:109]
	s_nop 0
	v_cvt_pk_bf16_f32 v22, v22, v23
	v_cvt_pk_bf16_f32 v23, v24, v25
	global_store_dwordx2 v[36:37], v[22:23], off offset:1024
	v_pk_fma_f32 v[20:21], v[130:131], v[20:21], v[114:115]
	v_pk_fma_f32 v[18:19], v[128:129], v[18:19], v[112:113]
	s_nop 0
	v_cvt_pk_bf16_f32 v18, v18, v19
	v_cvt_pk_bf16_f32 v19, v20, v21
	global_store_dwordx2 v[36:37], v[18:19], off offset:1536
	v_lshl_add_u64 v[36:37], v[36:37], 0, s[56:57]
	s_cbranch_scc0 .LBB0_784
